# last phase epilogue: the 15 later residual loads issued ahead of the first, result stores paced with vmcnt(6)
# baseline (speedup 1.0000x reference)
.LBB0_1746:
	s_andn2_b64 vcc, exec, s[8:9]
	s_cbranch_vccnz .LBB0_1748
	v_lshl_add_u32 v150, s26, 8, v1
	v_lshl_or_b32 v148, s51, 8, v153
	v_ashrrev_i32_e32 v151, 31, v150
	v_ashrrev_i32_e32 v149, 31, v148
	v_lshlrev_b64 v[146:147], 10, v[150:151]
	v_lshl_add_u64 v[146:147], v[146:147], 0, v[148:149]
	v_lshlrev_b64 v[162:163], 1, v[146:147]
	v_lshl_add_u64 v[158:159], s[78:79], 0, v[162:163]
	s_mov_b32 s95, 0
	s_mov_b32 s94, 0x100
	v_lshl_add_u64 v[242:243], v[158:159], 0, s[94:95]
	global_load_dwordx4 v[170:173], v[242:243], off
	s_mov_b32 s94, 0x8000
	v_lshl_add_u64 v[240:241], v[158:159], 0, s[94:95]
	global_load_dwordx4 v[174:177], v[240:241], off
	s_mov_b32 s94, 0x8100
	v_lshl_add_u64 v[242:243], v[158:159], 0, s[94:95]
	global_load_dwordx4 v[178:181], v[242:243], off
	s_mov_b32 s94, 0x10000
	v_lshl_add_u64 v[240:241], v[158:159], 0, s[94:95]
	global_load_dwordx4 v[182:185], v[240:241], off
	s_mov_b32 s94, 0x10100
	v_lshl_add_u64 v[242:243], v[158:159], 0, s[94:95]
	global_load_dwordx4 v[186:189], v[242:243], off
	s_mov_b32 s94, 0x18000
	v_lshl_add_u64 v[240:241], v[158:159], 0, s[94:95]
	global_load_dwordx4 v[190:193], v[240:241], off
	s_mov_b32 s94, 0x18100
	v_lshl_add_u64 v[242:243], v[158:159], 0, s[94:95]
	global_load_dwordx4 v[194:197], v[242:243], off
	s_mov_b32 s94, 0x40000
	v_lshl_add_u64 v[240:241], v[158:159], 0, s[94:95]
	global_load_dwordx4 v[200:203], v[240:241], off
	s_mov_b32 s94, 0x40100
	v_lshl_add_u64 v[242:243], v[158:159], 0, s[94:95]
	global_load_dwordx4 v[204:207], v[242:243], off
	s_mov_b32 s94, 0x48000
	v_lshl_add_u64 v[240:241], v[158:159], 0, s[94:95]
	global_load_dwordx4 v[208:211], v[240:241], off
	s_mov_b32 s94, 0x48100
	v_lshl_add_u64 v[242:243], v[158:159], 0, s[94:95]
	global_load_dwordx4 v[212:215], v[242:243], off
	s_mov_b32 s94, 0x50000
	v_lshl_add_u64 v[240:241], v[158:159], 0, s[94:95]
	global_load_dwordx4 v[216:219], v[240:241], off
	s_mov_b32 s94, 0x50100
	v_lshl_add_u64 v[242:243], v[158:159], 0, s[94:95]
	global_load_dwordx4 v[228:231], v[242:243], off
	s_mov_b32 s94, 0x58000
	v_lshl_add_u64 v[240:241], v[158:159], 0, s[94:95]
	global_load_dwordx4 v[232:235], v[240:241], off
	s_mov_b32 s94, 0x58100
	v_lshl_add_u64 v[242:243], v[158:159], 0, s[94:95]
	global_load_dwordx4 v[236:239], v[242:243], off
	global_load_dwordx4 v[158:161], v[158:159], off
	v_lshl_add_u64 v[164:165], v[146:147], 2, s[70:71]
	v_or_b32_e32 v162, 0x100, v162
	v_lshl_add_u64 v[162:163], s[78:79], 0, v[162:163]
	s_waitcnt vmcnt(0)
	v_lshlrev_b32_e32 v168, 16, v158
	v_and_b32_e32 v169, 0xffff0000, v158
	v_lshlrev_b32_e32 v158, 16, v159
	v_and_b32_e32 v159, 0xffff0000, v159
	v_lshlrev_b32_e32 v166, 16, v160
	v_and_b32_e32 v167, 0xffff0000, v160
	v_lshlrev_b32_e32 v160, 16, v161
	v_and_b32_e32 v161, 0xffff0000, v161
	v_pk_add_f32 v[128:129], v[128:129], v[158:159]
	v_pk_add_f32 v[126:127], v[126:127], v[168:169]
	v_pk_add_f32 v[124:125], v[124:125], v[160:161]
	v_pk_add_f32 v[122:123], v[122:123], v[166:167]
	global_store_dwordx4 v[164:165], v[126:129], off sc0 nt
	global_store_dwordx4 v[164:165], v[122:125], off offset:16 sc0 nt
	s_nop 1
	v_mov_b32_e32 v122, v170
	v_mov_b32_e32 v123, v171
	v_mov_b32_e32 v124, v172
	v_mov_b32_e32 v125, v173
	v_or_b32_e32 v126, 16, v150
	v_ashrrev_i32_e32 v127, 31, v126
	v_lshlrev_b64 v[126:127], 10, v[126:127]
	v_lshl_add_u64 v[126:127], v[126:127], 0, v[148:149]
	v_lshlrev_b64 v[128:129], 1, v[126:127]
	v_lshl_add_u64 v[158:159], s[78:79], 0, v[128:129]
	v_or_b32_e32 v128, 0x100, v128
	s_waitcnt vmcnt(6)
	v_lshlrev_b32_e32 v162, 16, v122
	v_and_b32_e32 v163, 0xffff0000, v122
	v_lshlrev_b32_e32 v122, 16, v123
	v_and_b32_e32 v123, 0xffff0000, v123
	v_lshlrev_b32_e32 v160, 16, v124
	v_and_b32_e32 v161, 0xffff0000, v124
	v_lshlrev_b32_e32 v124, 16, v125
	v_and_b32_e32 v125, 0xffff0000, v125
	v_pk_add_f32 v[120:121], v[120:121], v[122:123]
	v_pk_add_f32 v[118:119], v[118:119], v[162:163]
	v_pk_add_f32 v[116:117], v[116:117], v[124:125]
	v_pk_add_f32 v[114:115], v[114:115], v[160:161]
	global_store_dwordx4 v[164:165], v[118:121], off offset:512 sc0 nt
	global_store_dwordx4 v[164:165], v[114:117], off offset:528 sc0 nt
	s_nop 1
	v_mov_b32_e32 v114, v174
	v_mov_b32_e32 v115, v175
	v_mov_b32_e32 v116, v176
	v_mov_b32_e32 v117, v177
	v_lshl_add_u64 v[118:119], v[126:127], 2, s[70:71]
	v_lshl_add_u64 v[120:121], s[78:79], 0, v[128:129]
	s_waitcnt vmcnt(6)
	v_lshlrev_b32_e32 v124, 16, v114
	v_and_b32_e32 v125, 0xffff0000, v114
	v_lshlrev_b32_e32 v114, 16, v115
	v_and_b32_e32 v115, 0xffff0000, v115
	v_lshlrev_b32_e32 v122, 16, v116
	v_and_b32_e32 v123, 0xffff0000, v116
	v_lshlrev_b32_e32 v116, 16, v117
	v_and_b32_e32 v117, 0xffff0000, v117
	v_pk_add_f32 v[112:113], v[112:113], v[114:115]
	v_pk_add_f32 v[110:111], v[110:111], v[124:125]
	v_pk_add_f32 v[108:109], v[108:109], v[116:117]
	v_pk_add_f32 v[106:107], v[106:107], v[122:123]
	global_store_dwordx4 v[118:119], v[110:113], off sc0 nt
	global_store_dwordx4 v[118:119], v[106:109], off offset:16 sc0 nt
	s_nop 1
	v_mov_b32_e32 v106, v178
	v_mov_b32_e32 v107, v179
	v_mov_b32_e32 v108, v180
	v_mov_b32_e32 v109, v181
	v_or_b32_e32 v110, 32, v150
	v_ashrrev_i32_e32 v111, 31, v110
	v_lshlrev_b64 v[110:111], 10, v[110:111]
	v_lshl_add_u64 v[110:111], v[110:111], 0, v[148:149]
	v_lshlrev_b64 v[112:113], 1, v[110:111]
	v_lshl_add_u64 v[114:115], s[78:79], 0, v[112:113]
	v_or_b32_e32 v112, 0x100, v112
	s_waitcnt vmcnt(6)
	v_lshlrev_b32_e32 v120, 16, v106
	v_and_b32_e32 v121, 0xffff0000, v106
	v_lshlrev_b32_e32 v106, 16, v107
	v_and_b32_e32 v107, 0xffff0000, v107
	v_lshlrev_b32_e32 v116, 16, v108
	v_and_b32_e32 v117, 0xffff0000, v108
	v_lshlrev_b32_e32 v108, 16, v109
	v_and_b32_e32 v109, 0xffff0000, v109
	v_pk_add_f32 v[104:105], v[104:105], v[106:107]
	v_pk_add_f32 v[102:103], v[102:103], v[120:121]
	v_pk_add_f32 v[100:101], v[100:101], v[108:109]
	v_pk_add_f32 v[98:99], v[98:99], v[116:117]
	global_store_dwordx4 v[118:119], v[102:105], off offset:512 sc0 nt
	global_store_dwordx4 v[118:119], v[98:101], off offset:528 sc0 nt
	s_nop 1
	v_mov_b32_e32 v98, v182
	v_mov_b32_e32 v99, v183
	v_mov_b32_e32 v100, v184
	v_mov_b32_e32 v101, v185
	v_lshl_add_u64 v[102:103], v[110:111], 2, s[70:71]
	v_lshl_add_u64 v[104:105], s[78:79], 0, v[112:113]
	s_waitcnt vmcnt(6)
	v_lshlrev_b32_e32 v108, 16, v98
	v_and_b32_e32 v109, 0xffff0000, v98
	v_lshlrev_b32_e32 v98, 16, v99
	v_and_b32_e32 v99, 0xffff0000, v99
	v_lshlrev_b32_e32 v106, 16, v100
	v_and_b32_e32 v107, 0xffff0000, v100
	v_lshlrev_b32_e32 v100, 16, v101
	v_and_b32_e32 v101, 0xffff0000, v101
	v_pk_add_f32 v[96:97], v[96:97], v[98:99]
	v_pk_add_f32 v[94:95], v[94:95], v[108:109]
	v_pk_add_f32 v[92:93], v[92:93], v[100:101]
	v_pk_add_f32 v[90:91], v[90:91], v[106:107]
	global_store_dwordx4 v[102:103], v[94:97], off sc0 nt
	global_store_dwordx4 v[102:103], v[90:93], off offset:16 sc0 nt
	s_nop 1
	v_mov_b32_e32 v90, v186
	v_mov_b32_e32 v91, v187
	v_mov_b32_e32 v92, v188
	v_mov_b32_e32 v93, v189
	v_or_b32_e32 v94, 48, v150
	v_ashrrev_i32_e32 v95, 31, v94
	v_lshlrev_b64 v[94:95], 10, v[94:95]
	v_lshl_add_u64 v[94:95], v[94:95], 0, v[148:149]
	v_lshlrev_b64 v[96:97], 1, v[94:95]
	v_lshl_add_u64 v[98:99], s[78:79], 0, v[96:97]
	v_or_b32_e32 v96, 0x100, v96
	s_waitcnt vmcnt(6)
	v_lshlrev_b32_e32 v104, 16, v90
	v_and_b32_e32 v105, 0xffff0000, v90
	v_lshlrev_b32_e32 v90, 16, v91
	v_and_b32_e32 v91, 0xffff0000, v91
	v_lshlrev_b32_e32 v100, 16, v92
	v_and_b32_e32 v101, 0xffff0000, v92
	v_lshlrev_b32_e32 v92, 16, v93
	v_and_b32_e32 v93, 0xffff0000, v93
	v_pk_add_f32 v[88:89], v[88:89], v[90:91]
	v_pk_add_f32 v[86:87], v[86:87], v[104:105]
	v_pk_add_f32 v[84:85], v[84:85], v[92:93]
	v_pk_add_f32 v[82:83], v[82:83], v[100:101]
	global_store_dwordx4 v[102:103], v[86:89], off offset:512 sc0 nt
	global_store_dwordx4 v[102:103], v[82:85], off offset:528 sc0 nt
	s_nop 1
	v_mov_b32_e32 v82, v190
	v_mov_b32_e32 v83, v191
	v_mov_b32_e32 v84, v192
	v_mov_b32_e32 v85, v193
	v_lshl_add_u64 v[86:87], v[94:95], 2, s[70:71]
	v_lshl_add_u64 v[88:89], s[78:79], 0, v[96:97]
	s_waitcnt vmcnt(6)
	v_lshlrev_b32_e32 v92, 16, v82
	v_and_b32_e32 v93, 0xffff0000, v82
	v_lshlrev_b32_e32 v82, 16, v83
	v_and_b32_e32 v83, 0xffff0000, v83
	v_lshlrev_b32_e32 v90, 16, v84
	v_and_b32_e32 v91, 0xffff0000, v84
	v_lshlrev_b32_e32 v84, 16, v85
	v_and_b32_e32 v85, 0xffff0000, v85
	v_pk_add_f32 v[80:81], v[80:81], v[82:83]
	v_pk_add_f32 v[78:79], v[78:79], v[92:93]
	v_pk_add_f32 v[76:77], v[76:77], v[84:85]
	v_pk_add_f32 v[74:75], v[74:75], v[90:91]
	global_store_dwordx4 v[86:87], v[78:81], off sc0 nt
	global_store_dwordx4 v[86:87], v[74:77], off offset:16 sc0 nt
	s_nop 1
	v_mov_b32_e32 v74, v194
	v_mov_b32_e32 v75, v195
	v_mov_b32_e32 v76, v196
	v_mov_b32_e32 v77, v197
	v_lshl_add_u64 v[78:79], v[146:147], 0, s[10:11]
	v_lshlrev_b64 v[80:81], 1, v[78:79]
	v_lshl_add_u64 v[82:83], s[78:79], 0, v[80:81]
	v_or_b32_e32 v80, 0x100, v80
	s_waitcnt vmcnt(6)
	v_lshlrev_b32_e32 v88, 16, v74
	v_and_b32_e32 v89, 0xffff0000, v74
	v_lshlrev_b32_e32 v74, 16, v75
	v_and_b32_e32 v75, 0xffff0000, v75
	v_lshlrev_b32_e32 v84, 16, v76
	v_and_b32_e32 v85, 0xffff0000, v76
	v_lshlrev_b32_e32 v76, 16, v77
	v_and_b32_e32 v77, 0xffff0000, v77
	v_pk_add_f32 v[72:73], v[72:73], v[74:75]
	v_pk_add_f32 v[70:71], v[70:71], v[88:89]
	v_pk_add_f32 v[68:69], v[68:69], v[76:77]
	v_pk_add_f32 v[66:67], v[66:67], v[84:85]
	global_store_dwordx4 v[86:87], v[70:73], off offset:512 sc0 nt
	global_store_dwordx4 v[86:87], v[66:69], off offset:528 sc0 nt
	s_nop 1
	v_mov_b32_e32 v66, v200
	v_mov_b32_e32 v67, v201
	v_mov_b32_e32 v68, v202
	v_mov_b32_e32 v69, v203
	v_lshl_add_u64 v[70:71], v[78:79], 2, s[70:71]
	v_lshl_add_u64 v[72:73], s[78:79], 0, v[80:81]
	s_waitcnt vmcnt(6)
	v_lshlrev_b32_e32 v76, 16, v66
	v_and_b32_e32 v77, 0xffff0000, v66
	v_lshlrev_b32_e32 v66, 16, v67
	v_and_b32_e32 v67, 0xffff0000, v67
	v_lshlrev_b32_e32 v74, 16, v68
	v_and_b32_e32 v75, 0xffff0000, v68
	v_lshlrev_b32_e32 v68, 16, v69
	v_and_b32_e32 v69, 0xffff0000, v69
	v_pk_add_f32 v[64:65], v[64:65], v[66:67]
	v_pk_add_f32 v[62:63], v[62:63], v[76:77]
	v_pk_add_f32 v[60:61], v[60:61], v[68:69]
	v_pk_add_f32 v[58:59], v[58:59], v[74:75]
	global_store_dwordx4 v[70:71], v[62:65], off sc0 nt
	global_store_dwordx4 v[70:71], v[58:61], off offset:16 sc0 nt
	s_nop 1
	v_mov_b32_e32 v58, v204
	v_mov_b32_e32 v59, v205
	v_mov_b32_e32 v60, v206
	v_mov_b32_e32 v61, v207
	v_lshl_add_u64 v[62:63], v[146:147], 0, s[12:13]
	v_lshlrev_b64 v[64:65], 1, v[62:63]
	v_lshl_add_u64 v[66:67], s[78:79], 0, v[64:65]
	v_or_b32_e32 v64, 0x100, v64
	s_waitcnt vmcnt(6)
	v_lshlrev_b32_e32 v72, 16, v58
	v_and_b32_e32 v73, 0xffff0000, v58
	v_lshlrev_b32_e32 v58, 16, v59
	v_and_b32_e32 v59, 0xffff0000, v59
	v_lshlrev_b32_e32 v68, 16, v60
	v_and_b32_e32 v69, 0xffff0000, v60
	v_lshlrev_b32_e32 v60, 16, v61
	v_and_b32_e32 v61, 0xffff0000, v61
	v_pk_add_f32 v[56:57], v[56:57], v[58:59]
	v_pk_add_f32 v[54:55], v[54:55], v[72:73]
	v_pk_add_f32 v[52:53], v[52:53], v[60:61]
	v_pk_add_f32 v[50:51], v[50:51], v[68:69]
	global_store_dwordx4 v[70:71], v[54:57], off offset:512 sc0 nt
	global_store_dwordx4 v[70:71], v[50:53], off offset:528 sc0 nt
	s_nop 1
	v_mov_b32_e32 v50, v208
	v_mov_b32_e32 v51, v209
	v_mov_b32_e32 v52, v210
	v_mov_b32_e32 v53, v211
	v_lshl_add_u64 v[54:55], v[62:63], 2, s[70:71]
	v_lshl_add_u64 v[56:57], s[78:79], 0, v[64:65]
	s_waitcnt vmcnt(6)
	v_lshlrev_b32_e32 v60, 16, v50
	v_and_b32_e32 v61, 0xffff0000, v50
	v_lshlrev_b32_e32 v50, 16, v51
	v_and_b32_e32 v51, 0xffff0000, v51
	v_lshlrev_b32_e32 v58, 16, v52
	v_and_b32_e32 v59, 0xffff0000, v52
	v_lshlrev_b32_e32 v52, 16, v53
	v_and_b32_e32 v53, 0xffff0000, v53
	v_pk_add_f32 v[48:49], v[48:49], v[50:51]
	v_pk_add_f32 v[46:47], v[46:47], v[60:61]
	v_pk_add_f32 v[44:45], v[44:45], v[52:53]
	v_pk_add_f32 v[42:43], v[42:43], v[58:59]
	global_store_dwordx4 v[54:55], v[46:49], off sc0 nt
	global_store_dwordx4 v[54:55], v[42:45], off offset:16 sc0 nt
	s_nop 1
	v_mov_b32_e32 v42, v212
	v_mov_b32_e32 v43, v213
	v_mov_b32_e32 v44, v214
	v_mov_b32_e32 v45, v215
	v_lshl_add_u64 v[46:47], v[146:147], 0, s[14:15]
	v_lshlrev_b64 v[48:49], 1, v[46:47]
	v_lshl_add_u64 v[50:51], s[78:79], 0, v[48:49]
	v_or_b32_e32 v48, 0x100, v48
	s_waitcnt vmcnt(6)
	v_lshlrev_b32_e32 v56, 16, v42
	v_and_b32_e32 v57, 0xffff0000, v42
	v_lshlrev_b32_e32 v42, 16, v43
	v_and_b32_e32 v43, 0xffff0000, v43
	v_lshlrev_b32_e32 v52, 16, v44
	v_and_b32_e32 v53, 0xffff0000, v44
	v_lshlrev_b32_e32 v44, 16, v45
	v_and_b32_e32 v45, 0xffff0000, v45
	v_pk_add_f32 v[40:41], v[40:41], v[42:43]
	v_pk_add_f32 v[38:39], v[38:39], v[56:57]
	v_pk_add_f32 v[36:37], v[36:37], v[44:45]
	v_pk_add_f32 v[34:35], v[34:35], v[52:53]
	global_store_dwordx4 v[54:55], v[38:41], off offset:512 sc0 nt
	global_store_dwordx4 v[54:55], v[34:37], off offset:528 sc0 nt
	s_nop 1
	v_mov_b32_e32 v34, v216
	v_mov_b32_e32 v35, v217
	v_mov_b32_e32 v36, v218
	v_mov_b32_e32 v37, v219
	v_lshl_add_u64 v[38:39], v[46:47], 2, s[70:71]
	v_lshl_add_u64 v[40:41], s[78:79], 0, v[48:49]
	s_waitcnt vmcnt(6)
	v_lshlrev_b32_e32 v44, 16, v34
	v_and_b32_e32 v45, 0xffff0000, v34
	v_lshlrev_b32_e32 v34, 16, v35
	v_and_b32_e32 v35, 0xffff0000, v35
	v_lshlrev_b32_e32 v42, 16, v36
	v_and_b32_e32 v43, 0xffff0000, v36
	v_lshlrev_b32_e32 v36, 16, v37
	v_and_b32_e32 v37, 0xffff0000, v37
	v_pk_add_f32 v[32:33], v[32:33], v[34:35]
	v_pk_add_f32 v[30:31], v[30:31], v[44:45]
	v_pk_add_f32 v[28:29], v[28:29], v[36:37]
	v_pk_add_f32 v[26:27], v[26:27], v[42:43]
	global_store_dwordx4 v[38:39], v[30:33], off sc0 nt
	global_store_dwordx4 v[38:39], v[26:29], off offset:16 sc0 nt
	s_nop 1
	v_mov_b32_e32 v26, v228
	v_mov_b32_e32 v27, v229
	v_mov_b32_e32 v28, v230
	v_mov_b32_e32 v29, v231
	v_lshl_add_u64 v[30:31], v[146:147], 0, s[16:17]
	v_lshlrev_b64 v[32:33], 1, v[30:31]
	v_lshl_add_u64 v[34:35], s[78:79], 0, v[32:33]
	v_or_b32_e32 v32, 0x100, v32
	s_waitcnt vmcnt(6)
	v_lshlrev_b32_e32 v40, 16, v26
	v_and_b32_e32 v41, 0xffff0000, v26
	v_lshlrev_b32_e32 v26, 16, v27
	v_and_b32_e32 v27, 0xffff0000, v27
	v_lshlrev_b32_e32 v36, 16, v28
	v_and_b32_e32 v37, 0xffff0000, v28
	v_lshlrev_b32_e32 v28, 16, v29
	v_and_b32_e32 v29, 0xffff0000, v29
	v_pk_add_f32 v[24:25], v[24:25], v[26:27]
	v_pk_add_f32 v[22:23], v[22:23], v[40:41]
	v_pk_add_f32 v[20:21], v[20:21], v[28:29]
	v_pk_add_f32 v[18:19], v[18:19], v[36:37]
	global_store_dwordx4 v[38:39], v[22:25], off offset:512 sc0 nt
	global_store_dwordx4 v[38:39], v[18:21], off offset:528 sc0 nt
	s_nop 1
	v_mov_b32_e32 v18, v232
	v_mov_b32_e32 v19, v233
	v_mov_b32_e32 v20, v234
	v_mov_b32_e32 v21, v235
	v_lshl_add_u64 v[22:23], v[30:31], 2, s[70:71]
	v_lshl_add_u64 v[24:25], s[78:79], 0, v[32:33]
	s_waitcnt vmcnt(6)
	v_lshlrev_b32_e32 v28, 16, v18
	v_and_b32_e32 v29, 0xffff0000, v18
	v_lshlrev_b32_e32 v18, 16, v19
	v_and_b32_e32 v19, 0xffff0000, v19
	v_lshlrev_b32_e32 v26, 16, v20
	v_and_b32_e32 v27, 0xffff0000, v20
	v_lshlrev_b32_e32 v20, 16, v21
	v_and_b32_e32 v21, 0xffff0000, v21
	v_pk_add_f32 v[16:17], v[16:17], v[18:19]
	v_pk_add_f32 v[14:15], v[14:15], v[28:29]
	v_pk_add_f32 v[12:13], v[12:13], v[20:21]
	v_pk_add_f32 v[10:11], v[10:11], v[26:27]
	global_store_dwordx4 v[22:23], v[14:17], off sc0 nt
	global_store_dwordx4 v[22:23], v[10:13], off offset:16 sc0 nt
	s_nop 1
	v_mov_b32_e32 v10, v236
	v_mov_b32_e32 v11, v237
	v_mov_b32_e32 v12, v238
	v_mov_b32_e32 v13, v239
	s_waitcnt vmcnt(6)
	v_lshlrev_b32_e32 v16, 16, v10
	v_and_b32_e32 v17, 0xffff0000, v10
	v_lshlrev_b32_e32 v10, 16, v11
	v_and_b32_e32 v11, 0xffff0000, v11
	v_lshlrev_b32_e32 v14, 16, v12
	v_and_b32_e32 v15, 0xffff0000, v12
	v_lshlrev_b32_e32 v12, 16, v13
	v_and_b32_e32 v13, 0xffff0000, v13
	v_pk_add_f32 v[8:9], v[8:9], v[10:11]
	v_pk_add_f32 v[6:7], v[6:7], v[16:17]
	v_pk_add_f32 v[4:5], v[4:5], v[12:13]
	v_pk_add_f32 v[2:3], v[2:3], v[14:15]
	global_store_dwordx4 v[22:23], v[6:9], off offset:512 sc0 nt
	global_store_dwordx4 v[22:23], v[2:5], off offset:528 sc0 nt
